# prep: expert fp8 conversion loop prefetches the next row; thr histogram step rewritten (first pass merges equal bins into one LDS add); attn indexer abs folded into fma, no causal compares off the dia
# baseline (speedup 1.0000x reference)
; DI void phase_prep(const Params& p, char* smem) {
;     ...
;     for (int r = gw; r < 2 * 16384; r += nw) {
;       const int tbl = r >> 14, row = r & 16383;
;       const float* src = (tbl ? p.ex_up : p.ex_down) + (size_t)row * 1024 + lane * 16;
;       f32x4 v[4]; float mx = 0.f;
; #pragma unroll
;       for (int c = 0; c < 4; ++c) {
;         v[c] = *reinterpret_cast<const f32x4*>(src + c * 4);
.LBB0_11:
	v_writelane_b32 v255, s16, 5
	s_nop 1
	v_writelane_b32 v255, s17, 6
	s_or_b64 exec, exec, s[0:1]
	v_and_b32_e32 v162, 63, v166
	v_alignbit_b32 v22, v19, v18, 6
	s_mov_b32 s0, 0x8000
	v_cmp_gt_i32_e32 vcc, s0, v22
	v_lshlrev_b32_e32 v164, 4, v162
	v_mbcnt_lo_u32_b32 v97, -1, 0
	s_and_saveexec_b64 s[8:9], vcc
	s_cbranch_execz .LBB0_18
	v_mbcnt_hi_u32_b32 v2, -1, v97
	v_and_b32_e32 v1, 64, v2
	v_add_u32_e32 v3, 64, v1
	v_xor_b32_e32 v1, 32, v2
	v_cmp_lt_i32_e32 vcc, v1, v3
	v_xor_b32_e32 v4, 16, v2
	v_readlane_b32 s0, v255, 5
	v_cndmask_b32_e32 v1, v2, v1, vcc
	v_cmp_lt_i32_e32 vcc, v4, v3
	v_readlane_b32 s1, v255, 6
	v_ashrrev_i32_e32 v23, 31, v22
	v_cndmask_b32_e32 v4, v2, v4, vcc
	v_lshlrev_b32_e32 v32, 2, v4
	v_xor_b32_e32 v4, 8, v2
	v_cmp_lt_i32_e32 vcc, v4, v3
	s_lshr_b64 s[10:11], s[0:1], 6
	s_mov_b64 s[0:1], 0xa500000
	v_cndmask_b32_e32 v4, v2, v4, vcc
	v_lshlrev_b32_e32 v33, 2, v4
	v_xor_b32_e32 v4, 4, v2
	v_cmp_lt_i32_e32 vcc, v4, v3
	v_mov_b32_e32 v25, 0
	v_mov_b32_e32 v165, v25
	v_cndmask_b32_e32 v4, v2, v4, vcc
	v_lshlrev_b32_e32 v34, 2, v4
	v_xor_b32_e32 v4, 2, v2
	v_cmp_lt_i32_e32 vcc, v4, v3
	v_cmp_eq_u32_e64 s[4:5], 0, v162
	v_lshlrev_b32_e32 v1, 2, v1
	v_cndmask_b32_e32 v4, v2, v4, vcc
	v_lshlrev_b32_e32 v35, 2, v4
	v_xor_b32_e32 v4, 1, v2
	v_cmp_lt_i32_e32 vcc, v4, v3
	s_lshl_b32 s3, s10, 10
	s_mov_b64 s[14:15], 0
	v_cndmask_b32_e32 v2, v2, v4, vcc
	v_lshlrev_b32_e32 v36, 2, v2
	v_lshl_add_u64 v[2:3], v[22:23], 2, s[96:97]
	v_lshl_add_u64 v[26:27], v[2:3], 0, s[0:1]
	s_bfe_i64 s[0:1], s[10:11], 0x200000
	s_lshl_b64 s[12:13], s[0:1], 2
	v_lshlrev_b32_e32 v23, 10, v22
	s_movk_i32 s11, 0x4000
	s_waitcnt lgkmcnt(0)
	v_mov_b32_e32 v37, s45
	v_mov_b32_e32 v38, s43
	v_mov_b32_e32 v39, s44
	v_mov_b32_e32 v40, s42
	v_lshlrev_b32_e32 v28, 2, v164
	v_mov_b32_e32 v29, v25
	s_mov_b32 s18, 0x43600000
	s_mov_b32 s19, 0x800000
	s_mov_b32 s20, 0xc2fc0000
	v_mov_b32_e32 v41, 0x5000000
	v_bfrev_b32_e32 v42, 32
	s_movk_i32 s21, 0x7fff
	v_mov_b32_e32 v43, 0x42000000
	v_mov_b32_e32 v44, 0x42800000
	v_not_b32_e32 v45, 63
	v_cmp_gt_u32_e64 s[16:17], s11, v22
	v_and_b32_e32 v66, 0xfffc00, v23
	v_lshlrev_b32_e32 v66, 2, v66
	v_mov_b32_e32 v67, 0
	v_cndmask_b32_e64 v69, v37, v38, s[16:17]
	v_cndmask_b32_e64 v68, v39, v40, s[16:17]
	v_lshl_add_u64 v[68:69], v[68:69], 0, v[66:67]
	v_lshl_add_u64 v[68:69], v[68:69], 0, v[28:29]
	global_load_dwordx4 v[50:53], v[68:69], off
	global_load_dwordx4 v[54:57], v[68:69], off offset:16
	global_load_dwordx4 v[58:61], v[68:69], off offset:32
	global_load_dwordx4 v[62:65], v[68:69], off offset:48
	s_waitcnt vmcnt(0)
	s_branch .Lprep_e_enter

; DI void phase_prep(const Params& p, char* smem) {
;     ...
;     for (int r = gw; r < 2 * 16384; r += nw) {
;       const int tbl = r >> 14, row = r & 16383;
;       const float* src = (tbl ? p.ex_up : p.ex_down) + (size_t)row * 1024 + lane * 16;
;       f32x4 v[4]; float mx = 0.f;
; #pragma unroll
;       for (int c = 0; c < 4; ++c) {
;         v[c] = *reinterpret_cast<const f32x4*>(src + c * 4);
; #pragma unroll
;         for (int k = 0; k < 4; ++k) mx = fmaxf(mx, fabsf(v[c][k]));
;       }
; #pragma unroll
;       for (int d = 32; d >= 1; d >>= 1) mx = fmaxf(mx, __shfl_xor(mx, d));
;       float sc = (mx > 0.f) ? exp2f(floorf(log2f(224.f / mx))) : 1.f;
.LBB0_14:
	s_waitcnt vmcnt(2)
.Lprep_e_enter:
	v_cmp_gt_u32_e64 s[0:1], s11, v22
	v_and_b32_e32 v30, 0xfffc00, v23
	v_mov_b64_e32 v[14:15], v[50:51]
	v_mov_b64_e32 v[16:17], v[52:53]
	v_mov_b64_e32 v[10:11], v[54:55]
	v_mov_b64_e32 v[12:13], v[56:57]
	v_mov_b64_e32 v[6:7], v[58:59]
	v_mov_b64_e32 v[8:9], v[60:61]
	v_mov_b64_e32 v[2:3], v[62:63]
	v_mov_b64_e32 v[4:5], v[64:65]
	v_add_u32_e32 v70, s10, v22
	v_min_i32_e32 v70, s21, v70
	v_lshlrev_b32_e32 v71, 10, v70
	v_cmp_gt_u32_e64 s[16:17], s11, v70
	v_and_b32_e32 v66, 0xfffc00, v71
	v_lshlrev_b32_e32 v66, 2, v66
	v_mov_b32_e32 v67, 0
	v_cndmask_b32_e64 v69, v37, v38, s[16:17]
	v_cndmask_b32_e64 v68, v39, v40, s[16:17]
	v_lshl_add_u64 v[68:69], v[68:69], 0, v[66:67]
	v_lshl_add_u64 v[68:69], v[68:69], 0, v[28:29]
	global_load_dwordx4 v[50:53], v[68:69], off
	global_load_dwordx4 v[54:57], v[68:69], off offset:16
	global_load_dwordx4 v[58:61], v[68:69], off offset:32
	global_load_dwordx4 v[62:65], v[68:69], off offset:48
	v_mov_b32_e32 v46, 1.0
	v_max3_f32 v24, |v14|, 0, |v15|
	v_max3_f32 v24, v24, |v16|, |v17|
	v_max3_f32 v24, v24, |v10|, |v11|
	v_max3_f32 v24, v24, |v12|, |v13|
	v_max3_f32 v24, v24, |v6|, |v7|
	v_max3_f32 v24, v24, |v8|, |v9|
	v_max3_f32 v24, v24, |v2|, |v3|
	v_max3_f32 v24, v24, |v4|, |v5|
	ds_bpermute_b32 v31, v1, v24
	s_waitcnt lgkmcnt(0)
	v_max_f32_e32 v31, v31, v31
	v_max_f32_e32 v24, v24, v31
	ds_bpermute_b32 v31, v32, v24
	s_waitcnt lgkmcnt(0)
	v_max_f32_e32 v31, v31, v31
	v_max_f32_e32 v24, v24, v31
	ds_bpermute_b32 v31, v33, v24
	s_waitcnt lgkmcnt(0)
	v_max_f32_e32 v31, v31, v31
	v_max_f32_e32 v24, v24, v31
	ds_bpermute_b32 v31, v34, v24
	s_waitcnt lgkmcnt(0)
	v_max_f32_e32 v31, v31, v31
	v_max_f32_e32 v24, v24, v31
	ds_bpermute_b32 v31, v35, v24
	s_waitcnt lgkmcnt(0)
	v_max_f32_e32 v31, v31, v31
	v_max_f32_e32 v24, v24, v31
	ds_bpermute_b32 v31, v36, v24
	s_waitcnt lgkmcnt(0)
	v_max_f32_e32 v31, v31, v31
	v_max_f32_e32 v24, v24, v31
	v_cmp_lt_f32_e32 vcc, 0, v24
	s_and_saveexec_b64 s[16:17], vcc
	s_cbranch_execz .LBB0_16
	v_div_scale_f32 v31, s[22:23], v24, v24, s18
	v_rcp_f32_e32 v46, v31
	v_div_scale_f32 v47, vcc, s18, v24, s18
	v_fma_f32 v48, -v31, v46, 1.0
	v_fmac_f32_e32 v46, v48, v46
	v_mul_f32_e32 v48, v47, v46
	v_fma_f32 v49, -v31, v48, v47
	v_fmac_f32_e32 v48, v49, v46
	v_fma_f32 v31, -v31, v48, v47
	v_div_fmas_f32 v31, v31, v46, v48
	v_div_fixup_f32 v24, v31, v24, s18
	v_cmp_gt_f32_e32 vcc, s19, v24
	s_nop 1
	v_cndmask_b32_e64 v31, 0, 32, vcc
	v_ldexp_f32 v24, v24, v31
	v_log_f32_e32 v24, v24
	v_cndmask_b32_e32 v31, 0, v43, vcc
	v_sub_f32_e32 v24, v24, v31
	v_floor_f32_e32 v24, v24
	v_cmp_gt_f32_e32 vcc, s20, v24
	s_nop 1
	v_cndmask_b32_e32 v31, 0, v44, vcc
	v_add_f32_e32 v24, v24, v31
	v_exp_f32_e32 v24, v24
	v_cndmask_b32_e32 v31, 0, v45, vcc
	v_ldexp_f32 v46, v24, v31
